# grid barrier between ff2 of layer l and the (now in-projection-weights-only) phase 0 of layer l+1 removed: that phase 0 touches nothing ff2 uses
# speedup vs baseline: 1.0068x; 1.0068x over previous
; __global__ void __launch_bounds__(512, 2) mk_fwd(Args args) {
;     ...
;     for (int ph = args.ph_lo; ph < args.ph_hi; ++ph) {
;         if (ph == args.ph_lo + 1) cg::this_grid().sync();
;         else if (ph > args.ph_lo) xcd_barrier(bar);
.LBB0_10:
	s_cmp_eq_u32 s34, 9
	s_cbranch_scc1 .Lwp_nb
	s_cmp_eq_u32 s34, 18
	s_cbranch_scc1 .Lwp_nb
	s_cmp_eq_u32 s34, 27
	s_cbranch_scc0 .Lwp_bar
.Lwp_nb:
	s_cmp_gt_i32 s34, s58
	s_cbranch_scc0 .Lwp_bar
	v_readlane_b32 s0, v253, 49
	v_readlane_b32 s1, v253, 50
	s_nop 4
	s_load_dword s0, s[0:1], 0x0
	s_waitcnt lgkmcnt(0)
	s_cmpk_lg_i32 s0, 0x100
	s_cbranch_scc1 .Lwp_bar
	s_waitcnt vmcnt(0)
	s_barrier
	s_branch .LBB0_75
